# v78 + hand-written EpiRes epilogue in ph_down (x loads pipelined 4 rows deep, xb stores widened to dwordx4 via v_permlane16_swap, permlane row-sum reduction)
# speedup vs baseline: 1.0086x; 1.0019x over previous
; DI unsigned pk2(float lo, float hi) { unsigned r; asm("v_cvt_pk_bf16_f32 %0, %1, %2" : "=v"(r) : "v"(lo), "v"(hi)); return r; }
;     DI void operator()(const f32x4 (&acc)[2][2][4][2], const Unit& u, int wr, int wc, int fr, int fq) const {
;         const int col0 = u.pn * BM + wc * 32 + 4 * fq;
; #pragma unroll
;         for (int ai = 0; ai < 2; ++ai) {
;             const int rowa = u.pm * BM + ai * HALF + wr * 64 + fr;
;             f32x4 xo[4][2][2];
; #pragma unroll
;             for (int m = 0; m < 4; ++m)
; #pragma unroll
;                 for (int bj = 0; bj < 2; ++bj)
; #pragma unroll
;                     for (int n = 0; n < 2; ++n) xo[m][bj][n] = *(const f32x4*)(x + (size_t)(rowa + m * 16) * D + col0 + bj * HALF + n * 16);
;             asm volatile("" ::: "memory");
; #pragma unroll
;             for (int m = 0; m < 4; ++m) {
;                 const int row = rowa + m * 16;
;                 float* xr = x + (size_t)row * D + col0; bf16_t* br = xb + (size_t)row * D + col0;
;                 float ss = 0.f;
; #pragma unroll
;                 for (int bj = 0; bj < 2; ++bj)
; #pragma unroll
;                     for (int n = 0; n < 2; ++n) {
;                         const f32x4 xn = xo[m][bj][n] + acc[ai][bj][m][n] * s;
;                         *(f32x4*)(xr + bj * HALF + n * 16) = xn;
;                         u32x2 w; w.x = pk2(xn[0], xn[1]); w.y = pk2(xn[2], xn[3]);
;                         *(u32x2*)(br + bj * HALF + n * 16) = w;
;                         ss += (xn[0] * xn[0] + xn[1] * xn[1]) + (xn[2] * xn[2] + xn[3] * xn[3]);
;                     }
;                 ss += __shfl_xor(ss, 16); ss += __shfl_xor(ss, 32);
;                 if (fq == 0) slots[(size_t)row * 16 + u.pn * 4 + wc] = ss;
.LBB0_786:
	v_lshl_add_u32 v218, s72, 8, v1
	v_lshl_or_b32 v219, s12, 8, v216
	v_lshlrev_b32_e32 v220, 12, v218
	v_lshl_add_u32 v220, v219, 2, v220
	global_load_dwordx4 v[114:117], v220, s[46:47]
	global_load_dwordx4 v[118:121], v220, s[46:47] offset:64
	global_load_dwordx4 v[122:125], v220, s[46:47] offset:512
	global_load_dwordx4 v[126:129], v220, s[46:47] offset:576
	v_add_u32_e32 v149, 0x10000, v220
	global_load_dwordx4 v[162:165], v149, s[46:47]
	global_load_dwordx4 v[166:169], v149, s[46:47] offset:64
	global_load_dwordx4 v[170:173], v149, s[46:47] offset:512
	global_load_dwordx4 v[174:177], v149, s[46:47] offset:576
	v_add_u32_e32 v149, 0x20000, v220
	global_load_dwordx4 v[200:203], v149, s[46:47]
	global_load_dwordx4 v[204:207], v149, s[46:47] offset:64
	global_load_dwordx4 v[208:211], v149, s[46:47] offset:512
	global_load_dwordx4 v[212:215], v149, s[46:47] offset:576
	v_add_u32_e32 v149, 0x30000, v220
	global_load_dwordx4 v[134:137], v149, s[46:47]
	global_load_dwordx4 v[138:141], v149, s[46:47] offset:64
	global_load_dwordx4 v[186:189], v149, s[46:47] offset:512
	global_load_dwordx4 v[190:193], v149, s[46:47] offset:576
	v_lshlrev_b32_e32 v221, 11, v218
	v_and_b32_e32 v222, 16, v249
	v_lshl_add_u32 v221, v219, 1, v221
	v_lshrrev_b32_e32 v222, 1, v222
	s_lshl_b32 s58, s12, 4
	s_lshl_b32 s59, s70, 2
	v_lshl_add_u32 v222, v222, 1, v222
	s_add_i32 s58, s58, s59
	v_lshlrev_b32_e32 v223, 6, v218
	v_add_u32_e32 v221, v221, v222
	v_add_u32_e32 v223, s58, v223
	s_waitcnt vmcnt(12)
	v_pk_fma_f32 v[158:159], v[158:159], 0.5, v[114:115] op_sel_hi:[1,0,1]
	v_pk_fma_f32 v[160:161], v[160:161], 0.5, v[116:117] op_sel_hi:[1,0,1]
	v_pk_fma_f32 v[150:151], v[150:151], 0.5, v[118:119] op_sel_hi:[1,0,1]
	v_pk_fma_f32 v[152:153], v[152:153], 0.5, v[120:121] op_sel_hi:[1,0,1]
	v_pk_fma_f32 v[142:143], v[142:143], 0.5, v[122:123] op_sel_hi:[1,0,1]
	v_pk_fma_f32 v[144:145], v[144:145], 0.5, v[124:125] op_sel_hi:[1,0,1]
	v_pk_fma_f32 v[130:131], v[130:131], 0.5, v[126:127] op_sel_hi:[1,0,1]
	v_pk_fma_f32 v[132:133], v[132:133], 0.5, v[128:129] op_sel_hi:[1,0,1]
	v_add_u32_e32 v149, 0x80000, v220
	global_load_dwordx4 v[114:117], v149, s[46:47]
	global_load_dwordx4 v[118:121], v149, s[46:47] offset:64
	global_load_dwordx4 v[122:125], v149, s[46:47] offset:512
	global_load_dwordx4 v[126:129], v149, s[46:47] offset:576
	global_store_dwordx4 v220, v[158:161], s[46:47]
	global_store_dwordx4 v220, v[150:153], s[46:47] offset:64
	global_store_dwordx4 v220, v[142:145], s[46:47] offset:512
	global_store_dwordx4 v220, v[130:133], s[46:47] offset:576
	v_cvt_pk_bf16_f32 v224, v158, v159
	v_cvt_pk_bf16_f32 v225, v160, v161
	v_cvt_pk_bf16_f32 v226, v150, v151
	v_cvt_pk_bf16_f32 v227, v152, v153
	v_mul_f32_e32 v154, v159, v159
	v_mul_f32_e32 v155, v161, v161
	v_fmac_f32_e32 v154, v158, v158
	v_fmac_f32_e32 v155, v160, v160
	v_add_f32_e32 v156, v154, v155
	v_mul_f32_e32 v154, v151, v151
	v_mul_f32_e32 v155, v153, v153
	v_fmac_f32_e32 v154, v150, v150
	v_fmac_f32_e32 v155, v152, v152
	v_add_f32_e32 v154, v154, v155
	v_add_f32_e32 v156, v156, v154
	v_permlane16_swap_b32_e32 v224, v226
	v_permlane16_swap_b32_e32 v225, v227
	global_store_dwordx4 v221, v[224:227], s[50:51]
	v_cvt_pk_bf16_f32 v228, v142, v143
	v_cvt_pk_bf16_f32 v229, v144, v145
	v_cvt_pk_bf16_f32 v230, v130, v131
	v_cvt_pk_bf16_f32 v231, v132, v133
	v_mul_f32_e32 v154, v143, v143
	v_mul_f32_e32 v155, v145, v145
	v_fmac_f32_e32 v154, v142, v142
	v_fmac_f32_e32 v155, v144, v144
	v_add_f32_e32 v154, v154, v155
	v_add_f32_e32 v156, v156, v154
	v_mul_f32_e32 v154, v131, v131
	v_mul_f32_e32 v155, v133, v133
	v_fmac_f32_e32 v154, v130, v130
	v_fmac_f32_e32 v155, v132, v132
	v_add_f32_e32 v154, v154, v155
	v_add_f32_e32 v156, v156, v154
	v_permlane16_swap_b32_e32 v228, v230
	v_permlane16_swap_b32_e32 v229, v231
	global_store_dwordx4 v221, v[228:231], s[50:51] offset:256
	v_mov_b32_e32 v157, v156
	s_nop 1
	v_permlane16_swap_b32_e32 v157, v156
	v_add_f32_e32 v156, v157, v156
	v_mov_b32_e32 v157, v156
	s_nop 1
	v_permlane32_swap_b32_e32 v157, v156
	v_add_f32_e32 v156, v157, v156
	global_store_dword v223, v156, s[52:53]
	s_waitcnt vmcnt(19)
	v_pk_fma_f32 v[110:111], v[110:111], 0.5, v[162:163] op_sel_hi:[1,0,1]
	v_pk_fma_f32 v[112:113], v[112:113], 0.5, v[164:165] op_sel_hi:[1,0,1]
	v_pk_fma_f32 v[106:107], v[106:107], 0.5, v[166:167] op_sel_hi:[1,0,1]
	v_pk_fma_f32 v[108:109], v[108:109], 0.5, v[168:169] op_sel_hi:[1,0,1]
	v_pk_fma_f32 v[102:103], v[102:103], 0.5, v[170:171] op_sel_hi:[1,0,1]
	v_pk_fma_f32 v[104:105], v[104:105], 0.5, v[172:173] op_sel_hi:[1,0,1]
	v_pk_fma_f32 v[98:99], v[98:99], 0.5, v[174:175] op_sel_hi:[1,0,1]
	v_pk_fma_f32 v[100:101], v[100:101], 0.5, v[176:177] op_sel_hi:[1,0,1]
	v_add_u32_e32 v149, 0x90000, v220
	global_load_dwordx4 v[162:165], v149, s[46:47]
	global_load_dwordx4 v[166:169], v149, s[46:47] offset:64
	global_load_dwordx4 v[170:173], v149, s[46:47] offset:512
	global_load_dwordx4 v[174:177], v149, s[46:47] offset:576
	v_add_u32_e32 v146, 0x10000, v220
	v_add_u32_e32 v147, 0x8000, v221
	v_add_u32_e32 v148, 0x400, v223
	global_store_dwordx4 v146, v[110:113], s[46:47]
	global_store_dwordx4 v146, v[106:109], s[46:47] offset:64
	global_store_dwordx4 v146, v[102:105], s[46:47] offset:512
	global_store_dwordx4 v146, v[98:101], s[46:47] offset:576
	v_cvt_pk_bf16_f32 v224, v110, v111
	v_cvt_pk_bf16_f32 v225, v112, v113
	v_cvt_pk_bf16_f32 v226, v106, v107
	v_cvt_pk_bf16_f32 v227, v108, v109
	v_mul_f32_e32 v154, v111, v111
	v_mul_f32_e32 v155, v113, v113
	v_fmac_f32_e32 v154, v110, v110
	v_fmac_f32_e32 v155, v112, v112
	v_add_f32_e32 v156, v154, v155
	v_mul_f32_e32 v154, v107, v107
	v_mul_f32_e32 v155, v109, v109
	v_fmac_f32_e32 v154, v106, v106
	v_fmac_f32_e32 v155, v108, v108
	v_add_f32_e32 v154, v154, v155
	v_add_f32_e32 v156, v156, v154
	v_permlane16_swap_b32_e32 v224, v226
	v_permlane16_swap_b32_e32 v225, v227
	global_store_dwordx4 v147, v[224:227], s[50:51]
	v_cvt_pk_bf16_f32 v228, v102, v103
	v_cvt_pk_bf16_f32 v229, v104, v105
	v_cvt_pk_bf16_f32 v230, v98, v99
	v_cvt_pk_bf16_f32 v231, v100, v101
	v_mul_f32_e32 v154, v103, v103
	v_mul_f32_e32 v155, v105, v105
	v_fmac_f32_e32 v154, v102, v102
	v_fmac_f32_e32 v155, v104, v104
	v_add_f32_e32 v154, v154, v155
	v_add_f32_e32 v156, v156, v154
	v_mul_f32_e32 v154, v99, v99
	v_mul_f32_e32 v155, v101, v101
	v_fmac_f32_e32 v154, v98, v98
	v_fmac_f32_e32 v155, v100, v100
	v_add_f32_e32 v154, v154, v155
	v_add_f32_e32 v156, v156, v154
	v_permlane16_swap_b32_e32 v228, v230
	v_permlane16_swap_b32_e32 v229, v231
	global_store_dwordx4 v147, v[228:231], s[50:51] offset:256
	v_mov_b32_e32 v157, v156
	s_nop 1
	v_permlane16_swap_b32_e32 v157, v156
	v_add_f32_e32 v156, v157, v156
	v_mov_b32_e32 v157, v156
	s_nop 1
	v_permlane32_swap_b32_e32 v157, v156
	v_add_f32_e32 v156, v157, v156
	global_store_dword v148, v156, s[52:53]
	s_waitcnt vmcnt(26)
; DI unsigned pk2(float lo, float hi) { unsigned r; asm("v_cvt_pk_bf16_f32 %0, %1, %2" : "=v"(r) : "v"(lo), "v"(hi)); return r; }
;     DI void operator()(const f32x4 (&acc)[2][2][4][2], const Unit& u, int wr, int wc, int fr, int fq) const {
;     ...
;             for (int m = 0; m < 4; ++m) {
;                 const int row = rowa + m * 16;
;                 float* xr = x + (size_t)row * D + col0; bf16_t* br = xb + (size_t)row * D + col0;
;                 float ss = 0.f;
; #pragma unroll
;                 for (int bj = 0; bj < 2; ++bj)
; #pragma unroll
;                     for (int n = 0; n < 2; ++n) {
;                         const f32x4 xn = xo[m][bj][n] + acc[ai][bj][m][n] * s;
;                         *(f32x4*)(xr + bj * HALF + n * 16) = xn;
;                         u32x2 w; w.x = pk2(xn[0], xn[1]); w.y = pk2(xn[2], xn[3]);
;                         *(u32x2*)(br + bj * HALF + n * 16) = w;
;                         ss += (xn[0] * xn[0] + xn[1] * xn[1]) + (xn[2] * xn[2] + xn[3] * xn[3]);
;                     }
;                 ss += __shfl_xor(ss, 16); ss += __shfl_xor(ss, 32);
;                 if (fq == 0) slots[(size_t)row * 16 + u.pn * 4 + wc] = ss;
;             }
	v_pk_fma_f32 v[94:95], v[94:95], 0.5, v[200:201] op_sel_hi:[1,0,1]
	v_pk_fma_f32 v[96:97], v[96:97], 0.5, v[202:203] op_sel_hi:[1,0,1]
	v_pk_fma_f32 v[90:91], v[90:91], 0.5, v[204:205] op_sel_hi:[1,0,1]
	v_pk_fma_f32 v[92:93], v[92:93], 0.5, v[206:207] op_sel_hi:[1,0,1]
	v_pk_fma_f32 v[86:87], v[86:87], 0.5, v[208:209] op_sel_hi:[1,0,1]
	v_pk_fma_f32 v[88:89], v[88:89], 0.5, v[210:211] op_sel_hi:[1,0,1]
	v_pk_fma_f32 v[82:83], v[82:83], 0.5, v[212:213] op_sel_hi:[1,0,1]
	v_pk_fma_f32 v[84:85], v[84:85], 0.5, v[214:215] op_sel_hi:[1,0,1]
	v_add_u32_e32 v149, 0xa0000, v220
	global_load_dwordx4 v[200:203], v149, s[46:47]
	global_load_dwordx4 v[204:207], v149, s[46:47] offset:64
	global_load_dwordx4 v[208:211], v149, s[46:47] offset:512
	global_load_dwordx4 v[212:215], v149, s[46:47] offset:576
	v_add_u32_e32 v146, 0x20000, v220
	v_add_u32_e32 v147, 0x10000, v221
	v_add_u32_e32 v148, 0x800, v223
	global_store_dwordx4 v146, v[94:97], s[46:47]
	global_store_dwordx4 v146, v[90:93], s[46:47] offset:64
	global_store_dwordx4 v146, v[86:89], s[46:47] offset:512
	global_store_dwordx4 v146, v[82:85], s[46:47] offset:576
	v_cvt_pk_bf16_f32 v224, v94, v95
	v_cvt_pk_bf16_f32 v225, v96, v97
	v_cvt_pk_bf16_f32 v226, v90, v91
	v_cvt_pk_bf16_f32 v227, v92, v93
	v_mul_f32_e32 v154, v95, v95
	v_mul_f32_e32 v155, v97, v97
	v_fmac_f32_e32 v154, v94, v94
	v_fmac_f32_e32 v155, v96, v96
	v_add_f32_e32 v156, v154, v155
	v_mul_f32_e32 v154, v91, v91
	v_mul_f32_e32 v155, v93, v93
	v_fmac_f32_e32 v154, v90, v90
	v_fmac_f32_e32 v155, v92, v92
	v_add_f32_e32 v154, v154, v155
	v_add_f32_e32 v156, v156, v154
	v_permlane16_swap_b32_e32 v224, v226
	v_permlane16_swap_b32_e32 v225, v227
	global_store_dwordx4 v147, v[224:227], s[50:51]
	v_cvt_pk_bf16_f32 v228, v86, v87
	v_cvt_pk_bf16_f32 v229, v88, v89
	v_cvt_pk_bf16_f32 v230, v82, v83
	v_cvt_pk_bf16_f32 v231, v84, v85
	v_mul_f32_e32 v154, v87, v87
	v_mul_f32_e32 v155, v89, v89
	v_fmac_f32_e32 v154, v86, v86
	v_fmac_f32_e32 v155, v88, v88
	v_add_f32_e32 v154, v154, v155
	v_add_f32_e32 v156, v156, v154
	v_mul_f32_e32 v154, v83, v83
	v_mul_f32_e32 v155, v85, v85
	v_fmac_f32_e32 v154, v82, v82
	v_fmac_f32_e32 v155, v84, v84
	v_add_f32_e32 v154, v154, v155
	v_add_f32_e32 v156, v156, v154
	v_permlane16_swap_b32_e32 v228, v230
	v_permlane16_swap_b32_e32 v229, v231
	global_store_dwordx4 v147, v[228:231], s[50:51] offset:256
	v_mov_b32_e32 v157, v156
	s_nop 1
	v_permlane16_swap_b32_e32 v157, v156
	v_add_f32_e32 v156, v157, v156
	v_mov_b32_e32 v157, v156
	s_nop 1
	v_permlane32_swap_b32_e32 v157, v156
	v_add_f32_e32 v156, v157, v156
	global_store_dword v148, v156, s[52:53]
	s_waitcnt vmcnt(33)
	v_pk_fma_f32 v[78:79], v[78:79], 0.5, v[134:135] op_sel_hi:[1,0,1]
	v_pk_fma_f32 v[80:81], v[80:81], 0.5, v[136:137] op_sel_hi:[1,0,1]
	v_pk_fma_f32 v[74:75], v[74:75], 0.5, v[138:139] op_sel_hi:[1,0,1]
	v_pk_fma_f32 v[76:77], v[76:77], 0.5, v[140:141] op_sel_hi:[1,0,1]
	v_pk_fma_f32 v[70:71], v[70:71], 0.5, v[186:187] op_sel_hi:[1,0,1]
	v_pk_fma_f32 v[72:73], v[72:73], 0.5, v[188:189] op_sel_hi:[1,0,1]
	v_pk_fma_f32 v[66:67], v[66:67], 0.5, v[190:191] op_sel_hi:[1,0,1]
	v_pk_fma_f32 v[68:69], v[68:69], 0.5, v[192:193] op_sel_hi:[1,0,1]
	v_add_u32_e32 v149, 0xb0000, v220
	global_load_dwordx4 v[134:137], v149, s[46:47]
	global_load_dwordx4 v[138:141], v149, s[46:47] offset:64
	global_load_dwordx4 v[186:189], v149, s[46:47] offset:512
	global_load_dwordx4 v[190:193], v149, s[46:47] offset:576
	v_add_u32_e32 v146, 0x30000, v220
	v_add_u32_e32 v147, 0x18000, v221
	v_add_u32_e32 v148, 0xc00, v223
	global_store_dwordx4 v146, v[78:81], s[46:47]
	global_store_dwordx4 v146, v[74:77], s[46:47] offset:64
	global_store_dwordx4 v146, v[70:73], s[46:47] offset:512
	global_store_dwordx4 v146, v[66:69], s[46:47] offset:576
	v_cvt_pk_bf16_f32 v224, v78, v79
	v_cvt_pk_bf16_f32 v225, v80, v81
	v_cvt_pk_bf16_f32 v226, v74, v75
	v_cvt_pk_bf16_f32 v227, v76, v77
	v_mul_f32_e32 v154, v79, v79
	v_mul_f32_e32 v155, v81, v81
	v_fmac_f32_e32 v154, v78, v78
	v_fmac_f32_e32 v155, v80, v80
	v_add_f32_e32 v156, v154, v155
	v_mul_f32_e32 v154, v75, v75
	v_mul_f32_e32 v155, v77, v77
	v_fmac_f32_e32 v154, v74, v74
	v_fmac_f32_e32 v155, v76, v76
	v_add_f32_e32 v154, v154, v155
	v_add_f32_e32 v156, v156, v154
	v_permlane16_swap_b32_e32 v224, v226
	v_permlane16_swap_b32_e32 v225, v227
	global_store_dwordx4 v147, v[224:227], s[50:51]
	v_cvt_pk_bf16_f32 v228, v70, v71
	v_cvt_pk_bf16_f32 v229, v72, v73
	v_cvt_pk_bf16_f32 v230, v66, v67
	v_cvt_pk_bf16_f32 v231, v68, v69
	v_mul_f32_e32 v154, v71, v71
	v_mul_f32_e32 v155, v73, v73
	v_fmac_f32_e32 v154, v70, v70
	v_fmac_f32_e32 v155, v72, v72
	v_add_f32_e32 v154, v154, v155
	v_add_f32_e32 v156, v156, v154
	v_mul_f32_e32 v154, v67, v67
	v_mul_f32_e32 v155, v69, v69
	v_fmac_f32_e32 v154, v66, v66
	v_fmac_f32_e32 v155, v68, v68
	v_add_f32_e32 v154, v154, v155
	v_add_f32_e32 v156, v156, v154
	v_permlane16_swap_b32_e32 v228, v230
	v_permlane16_swap_b32_e32 v229, v231
	global_store_dwordx4 v147, v[228:231], s[50:51] offset:256
	v_mov_b32_e32 v157, v156
	s_nop 1
	v_permlane16_swap_b32_e32 v157, v156
	v_add_f32_e32 v156, v157, v156
	v_mov_b32_e32 v157, v156
	s_nop 1
	v_permlane32_swap_b32_e32 v157, v156
	v_add_f32_e32 v156, v157, v156
	global_store_dword v148, v156, s[52:53]
	s_waitcnt vmcnt(40)
; DI unsigned pk2(float lo, float hi) { unsigned r; asm("v_cvt_pk_bf16_f32 %0, %1, %2" : "=v"(r) : "v"(lo), "v"(hi)); return r; }
;     DI void operator()(const f32x4 (&acc)[2][2][4][2], const Unit& u, int wr, int wc, int fr, int fq) const {
;     ...
;             for (int m = 0; m < 4; ++m) {
;                 const int row = rowa + m * 16;
;                 float* xr = x + (size_t)row * D + col0; bf16_t* br = xb + (size_t)row * D + col0;
;                 float ss = 0.f;
; #pragma unroll
;                 for (int bj = 0; bj < 2; ++bj)
; #pragma unroll
;                     for (int n = 0; n < 2; ++n) {
;                         const f32x4 xn = xo[m][bj][n] + acc[ai][bj][m][n] * s;
;                         *(f32x4*)(xr + bj * HALF + n * 16) = xn;
;                         u32x2 w; w.x = pk2(xn[0], xn[1]); w.y = pk2(xn[2], xn[3]);
;                         *(u32x2*)(br + bj * HALF + n * 16) = w;
;                         ss += (xn[0] * xn[0] + xn[1] * xn[1]) + (xn[2] * xn[2] + xn[3] * xn[3]);
;                     }
;                 ss += __shfl_xor(ss, 16); ss += __shfl_xor(ss, 32);
;                 if (fq == 0) slots[(size_t)row * 16 + u.pn * 4 + wc] = ss;
;             }
	v_pk_fma_f32 v[62:63], v[62:63], 0.5, v[114:115] op_sel_hi:[1,0,1]
	v_pk_fma_f32 v[64:65], v[64:65], 0.5, v[116:117] op_sel_hi:[1,0,1]
	v_pk_fma_f32 v[58:59], v[58:59], 0.5, v[118:119] op_sel_hi:[1,0,1]
	v_pk_fma_f32 v[60:61], v[60:61], 0.5, v[120:121] op_sel_hi:[1,0,1]
	v_pk_fma_f32 v[54:55], v[54:55], 0.5, v[122:123] op_sel_hi:[1,0,1]
	v_pk_fma_f32 v[56:57], v[56:57], 0.5, v[124:125] op_sel_hi:[1,0,1]
	v_pk_fma_f32 v[50:51], v[50:51], 0.5, v[126:127] op_sel_hi:[1,0,1]
	v_pk_fma_f32 v[52:53], v[52:53], 0.5, v[128:129] op_sel_hi:[1,0,1]
	v_add_u32_e32 v146, 0x80000, v220
	v_add_u32_e32 v147, 0x40000, v221
	v_add_u32_e32 v148, 0x2000, v223
	global_store_dwordx4 v146, v[62:65], s[46:47]
	global_store_dwordx4 v146, v[58:61], s[46:47] offset:64
	global_store_dwordx4 v146, v[54:57], s[46:47] offset:512
	global_store_dwordx4 v146, v[50:53], s[46:47] offset:576
	v_cvt_pk_bf16_f32 v224, v62, v63
	v_cvt_pk_bf16_f32 v225, v64, v65
	v_cvt_pk_bf16_f32 v226, v58, v59
	v_cvt_pk_bf16_f32 v227, v60, v61
	v_mul_f32_e32 v154, v63, v63
	v_mul_f32_e32 v155, v65, v65
	v_fmac_f32_e32 v154, v62, v62
	v_fmac_f32_e32 v155, v64, v64
	v_add_f32_e32 v156, v154, v155
	v_mul_f32_e32 v154, v59, v59
	v_mul_f32_e32 v155, v61, v61
	v_fmac_f32_e32 v154, v58, v58
	v_fmac_f32_e32 v155, v60, v60
	v_add_f32_e32 v154, v154, v155
	v_add_f32_e32 v156, v156, v154
	v_permlane16_swap_b32_e32 v224, v226
	v_permlane16_swap_b32_e32 v225, v227
	global_store_dwordx4 v147, v[224:227], s[50:51]
	v_cvt_pk_bf16_f32 v228, v54, v55
	v_cvt_pk_bf16_f32 v229, v56, v57
	v_cvt_pk_bf16_f32 v230, v50, v51
	v_cvt_pk_bf16_f32 v231, v52, v53
	v_mul_f32_e32 v154, v55, v55
	v_mul_f32_e32 v155, v57, v57
	v_fmac_f32_e32 v154, v54, v54
	v_fmac_f32_e32 v155, v56, v56
	v_add_f32_e32 v154, v154, v155
	v_add_f32_e32 v156, v156, v154
	v_mul_f32_e32 v154, v51, v51
	v_mul_f32_e32 v155, v53, v53
	v_fmac_f32_e32 v154, v50, v50
	v_fmac_f32_e32 v155, v52, v52
	v_add_f32_e32 v154, v154, v155
	v_add_f32_e32 v156, v156, v154
	v_permlane16_swap_b32_e32 v228, v230
	v_permlane16_swap_b32_e32 v229, v231
	global_store_dwordx4 v147, v[228:231], s[50:51] offset:256
	v_mov_b32_e32 v157, v156
	s_nop 1
	v_permlane16_swap_b32_e32 v157, v156
	v_add_f32_e32 v156, v157, v156
	v_mov_b32_e32 v157, v156
	s_nop 1
	v_permlane32_swap_b32_e32 v157, v156
	v_add_f32_e32 v156, v157, v156
	global_store_dword v148, v156, s[52:53]
	s_waitcnt vmcnt(36)
	v_pk_fma_f32 v[46:47], v[46:47], 0.5, v[162:163] op_sel_hi:[1,0,1]
	v_pk_fma_f32 v[48:49], v[48:49], 0.5, v[164:165] op_sel_hi:[1,0,1]
	v_pk_fma_f32 v[42:43], v[42:43], 0.5, v[166:167] op_sel_hi:[1,0,1]
	v_pk_fma_f32 v[44:45], v[44:45], 0.5, v[168:169] op_sel_hi:[1,0,1]
	v_pk_fma_f32 v[38:39], v[38:39], 0.5, v[170:171] op_sel_hi:[1,0,1]
	v_pk_fma_f32 v[40:41], v[40:41], 0.5, v[172:173] op_sel_hi:[1,0,1]
	v_pk_fma_f32 v[34:35], v[34:35], 0.5, v[174:175] op_sel_hi:[1,0,1]
	v_pk_fma_f32 v[36:37], v[36:37], 0.5, v[176:177] op_sel_hi:[1,0,1]
	v_add_u32_e32 v146, 0x90000, v220
	v_add_u32_e32 v147, 0x48000, v221
	v_add_u32_e32 v148, 0x2400, v223
	global_store_dwordx4 v146, v[46:49], s[46:47]
	global_store_dwordx4 v146, v[42:45], s[46:47] offset:64
	global_store_dwordx4 v146, v[38:41], s[46:47] offset:512
	global_store_dwordx4 v146, v[34:37], s[46:47] offset:576
	v_cvt_pk_bf16_f32 v224, v46, v47
	v_cvt_pk_bf16_f32 v225, v48, v49
	v_cvt_pk_bf16_f32 v226, v42, v43
	v_cvt_pk_bf16_f32 v227, v44, v45
	v_mul_f32_e32 v154, v47, v47
	v_mul_f32_e32 v155, v49, v49
	v_fmac_f32_e32 v154, v46, v46
	v_fmac_f32_e32 v155, v48, v48
	v_add_f32_e32 v156, v154, v155
	v_mul_f32_e32 v154, v43, v43
	v_mul_f32_e32 v155, v45, v45
	v_fmac_f32_e32 v154, v42, v42
	v_fmac_f32_e32 v155, v44, v44
	v_add_f32_e32 v154, v154, v155
	v_add_f32_e32 v156, v156, v154
	v_permlane16_swap_b32_e32 v224, v226
	v_permlane16_swap_b32_e32 v225, v227
	global_store_dwordx4 v147, v[224:227], s[50:51]
	v_cvt_pk_bf16_f32 v228, v38, v39
	v_cvt_pk_bf16_f32 v229, v40, v41
	v_cvt_pk_bf16_f32 v230, v34, v35
	v_cvt_pk_bf16_f32 v231, v36, v37
	v_mul_f32_e32 v154, v39, v39
	v_mul_f32_e32 v155, v41, v41
	v_fmac_f32_e32 v154, v38, v38
	v_fmac_f32_e32 v155, v40, v40
	v_add_f32_e32 v154, v154, v155
	v_add_f32_e32 v156, v156, v154
	v_mul_f32_e32 v154, v35, v35
	v_mul_f32_e32 v155, v37, v37
	v_fmac_f32_e32 v154, v34, v34
	v_fmac_f32_e32 v155, v36, v36
	v_add_f32_e32 v154, v154, v155
	v_add_f32_e32 v156, v156, v154
	v_permlane16_swap_b32_e32 v228, v230
	v_permlane16_swap_b32_e32 v229, v231
	global_store_dwordx4 v147, v[228:231], s[50:51] offset:256
	v_mov_b32_e32 v157, v156
	s_nop 1
	v_permlane16_swap_b32_e32 v157, v156
	v_add_f32_e32 v156, v157, v156
	v_mov_b32_e32 v157, v156
	s_nop 1
	v_permlane32_swap_b32_e32 v157, v156
	v_add_f32_e32 v156, v157, v156
	global_store_dword v148, v156, s[52:53]
	s_waitcnt vmcnt(32)
; DI unsigned pk2(float lo, float hi) { unsigned r; asm("v_cvt_pk_bf16_f32 %0, %1, %2" : "=v"(r) : "v"(lo), "v"(hi)); return r; }
;     DI void operator()(const f32x4 (&acc)[2][2][4][2], const Unit& u, int wr, int wc, int fr, int fq) const {
;     ...
;             for (int m = 0; m < 4; ++m) {
;                 const int row = rowa + m * 16;
;                 float* xr = x + (size_t)row * D + col0; bf16_t* br = xb + (size_t)row * D + col0;
;                 float ss = 0.f;
; #pragma unroll
;                 for (int bj = 0; bj < 2; ++bj)
; #pragma unroll
;                     for (int n = 0; n < 2; ++n) {
;                         const f32x4 xn = xo[m][bj][n] + acc[ai][bj][m][n] * s;
;                         *(f32x4*)(xr + bj * HALF + n * 16) = xn;
;                         u32x2 w; w.x = pk2(xn[0], xn[1]); w.y = pk2(xn[2], xn[3]);
;                         *(u32x2*)(br + bj * HALF + n * 16) = w;
;                         ss += (xn[0] * xn[0] + xn[1] * xn[1]) + (xn[2] * xn[2] + xn[3] * xn[3]);
;                     }
;                 ss += __shfl_xor(ss, 16); ss += __shfl_xor(ss, 32);
;                 if (fq == 0) slots[(size_t)row * 16 + u.pn * 4 + wc] = ss;
;             }
	v_pk_fma_f32 v[30:31], v[30:31], 0.5, v[200:201] op_sel_hi:[1,0,1]
	v_pk_fma_f32 v[32:33], v[32:33], 0.5, v[202:203] op_sel_hi:[1,0,1]
	v_pk_fma_f32 v[26:27], v[26:27], 0.5, v[204:205] op_sel_hi:[1,0,1]
	v_pk_fma_f32 v[28:29], v[28:29], 0.5, v[206:207] op_sel_hi:[1,0,1]
	v_pk_fma_f32 v[22:23], v[22:23], 0.5, v[208:209] op_sel_hi:[1,0,1]
	v_pk_fma_f32 v[24:25], v[24:25], 0.5, v[210:211] op_sel_hi:[1,0,1]
	v_pk_fma_f32 v[18:19], v[18:19], 0.5, v[212:213] op_sel_hi:[1,0,1]
	v_pk_fma_f32 v[20:21], v[20:21], 0.5, v[214:215] op_sel_hi:[1,0,1]
	v_add_u32_e32 v146, 0xa0000, v220
	v_add_u32_e32 v147, 0x50000, v221
	v_add_u32_e32 v148, 0x2800, v223
	global_store_dwordx4 v146, v[30:33], s[46:47]
	global_store_dwordx4 v146, v[26:29], s[46:47] offset:64
	global_store_dwordx4 v146, v[22:25], s[46:47] offset:512
	global_store_dwordx4 v146, v[18:21], s[46:47] offset:576
	v_cvt_pk_bf16_f32 v224, v30, v31
	v_cvt_pk_bf16_f32 v225, v32, v33
	v_cvt_pk_bf16_f32 v226, v26, v27
	v_cvt_pk_bf16_f32 v227, v28, v29
	v_mul_f32_e32 v154, v31, v31
	v_mul_f32_e32 v155, v33, v33
	v_fmac_f32_e32 v154, v30, v30
	v_fmac_f32_e32 v155, v32, v32
	v_add_f32_e32 v156, v154, v155
	v_mul_f32_e32 v154, v27, v27
	v_mul_f32_e32 v155, v29, v29
	v_fmac_f32_e32 v154, v26, v26
	v_fmac_f32_e32 v155, v28, v28
	v_add_f32_e32 v154, v154, v155
	v_add_f32_e32 v156, v156, v154
	v_permlane16_swap_b32_e32 v224, v226
	v_permlane16_swap_b32_e32 v225, v227
	global_store_dwordx4 v147, v[224:227], s[50:51]
	v_cvt_pk_bf16_f32 v228, v22, v23
	v_cvt_pk_bf16_f32 v229, v24, v25
	v_cvt_pk_bf16_f32 v230, v18, v19
	v_cvt_pk_bf16_f32 v231, v20, v21
	v_mul_f32_e32 v154, v23, v23
	v_mul_f32_e32 v155, v25, v25
	v_fmac_f32_e32 v154, v22, v22
	v_fmac_f32_e32 v155, v24, v24
	v_add_f32_e32 v154, v154, v155
	v_add_f32_e32 v156, v156, v154
	v_mul_f32_e32 v154, v19, v19
	v_mul_f32_e32 v155, v21, v21
	v_fmac_f32_e32 v154, v18, v18
	v_fmac_f32_e32 v155, v20, v20
	v_add_f32_e32 v154, v154, v155
	v_add_f32_e32 v156, v156, v154
	v_permlane16_swap_b32_e32 v228, v230
	v_permlane16_swap_b32_e32 v229, v231
	global_store_dwordx4 v147, v[228:231], s[50:51] offset:256
	v_mov_b32_e32 v157, v156
	s_nop 1
	v_permlane16_swap_b32_e32 v157, v156
	v_add_f32_e32 v156, v157, v156
	v_mov_b32_e32 v157, v156
	s_nop 1
	v_permlane32_swap_b32_e32 v157, v156
	v_add_f32_e32 v156, v157, v156
	global_store_dword v148, v156, s[52:53]
	s_waitcnt vmcnt(28)
	v_pk_fma_f32 v[14:15], v[14:15], 0.5, v[134:135] op_sel_hi:[1,0,1]
	v_pk_fma_f32 v[16:17], v[16:17], 0.5, v[136:137] op_sel_hi:[1,0,1]
	v_pk_fma_f32 v[10:11], v[10:11], 0.5, v[138:139] op_sel_hi:[1,0,1]
	v_pk_fma_f32 v[12:13], v[12:13], 0.5, v[140:141] op_sel_hi:[1,0,1]
	v_pk_fma_f32 v[6:7], v[6:7], 0.5, v[186:187] op_sel_hi:[1,0,1]
	v_pk_fma_f32 v[8:9], v[8:9], 0.5, v[188:189] op_sel_hi:[1,0,1]
	v_pk_fma_f32 v[2:3], v[2:3], 0.5, v[190:191] op_sel_hi:[1,0,1]
	v_pk_fma_f32 v[4:5], v[4:5], 0.5, v[192:193] op_sel_hi:[1,0,1]
	v_add_u32_e32 v146, 0xb0000, v220
	v_add_u32_e32 v147, 0x58000, v221
	v_add_u32_e32 v148, 0x2c00, v223
	global_store_dwordx4 v146, v[14:17], s[46:47]
	global_store_dwordx4 v146, v[10:13], s[46:47] offset:64
	global_store_dwordx4 v146, v[6:9], s[46:47] offset:512
	global_store_dwordx4 v146, v[2:5], s[46:47] offset:576
	v_cvt_pk_bf16_f32 v224, v14, v15
	v_cvt_pk_bf16_f32 v225, v16, v17
	v_cvt_pk_bf16_f32 v226, v10, v11
	v_cvt_pk_bf16_f32 v227, v12, v13
	v_mul_f32_e32 v154, v15, v15
	v_mul_f32_e32 v155, v17, v17
	v_fmac_f32_e32 v154, v14, v14
	v_fmac_f32_e32 v155, v16, v16
	v_add_f32_e32 v156, v154, v155
	v_mul_f32_e32 v154, v11, v11
	v_mul_f32_e32 v155, v13, v13
	v_fmac_f32_e32 v154, v10, v10
	v_fmac_f32_e32 v155, v12, v12
	v_add_f32_e32 v154, v154, v155
	v_add_f32_e32 v156, v156, v154
	v_permlane16_swap_b32_e32 v224, v226
	v_permlane16_swap_b32_e32 v225, v227
	global_store_dwordx4 v147, v[224:227], s[50:51]
	v_cvt_pk_bf16_f32 v228, v6, v7
	v_cvt_pk_bf16_f32 v229, v8, v9
	v_cvt_pk_bf16_f32 v230, v2, v3
	v_cvt_pk_bf16_f32 v231, v4, v5
	v_mul_f32_e32 v154, v7, v7
	v_mul_f32_e32 v155, v9, v9
	v_fmac_f32_e32 v154, v6, v6
	v_fmac_f32_e32 v155, v8, v8
	v_add_f32_e32 v154, v154, v155
	v_add_f32_e32 v156, v156, v154
	v_mul_f32_e32 v154, v3, v3
	v_mul_f32_e32 v155, v5, v5
	v_fmac_f32_e32 v154, v2, v2
	v_fmac_f32_e32 v155, v4, v4
	v_add_f32_e32 v154, v154, v155
	v_add_f32_e32 v156, v156, v154
	v_permlane16_swap_b32_e32 v228, v230
	v_permlane16_swap_b32_e32 v229, v231
	global_store_dwordx4 v147, v[228:231], s[50:51] offset:256
	v_mov_b32_e32 v157, v156
	s_nop 1
	v_permlane16_swap_b32_e32 v157, v156
	v_add_f32_e32 v156, v157, v156
	v_mov_b32_e32 v157, v156
	s_nop 1
	v_permlane32_swap_b32_e32 v157, v156
	v_add_f32_e32 v156, v157, v156
	global_store_dword v148, v156, s[52:53]
	s_and_b64 vcc, exec, s[6:7]
	s_mov_b64 s[6:7], -1
	s_cbranch_vccnz .LBB0_771
	s_andn2_b64 vcc, exec, s[48:49]
	s_cbranch_vccnz .LBB0_770
	s_barrier
	s_branch .LBB0_770
